# PL-gate epilogue: dword touch loads for row groups 1-7 of the residual and pp tiles issued right after group 0's loads (L2 warm-up, no registers held)
# baseline (speedup 1.0000x reference)
; #define LAS __attribute__((address_space(3)))
; #define GAS __attribute__((address_space(1)))
; __device__ __forceinline__ unsigned cvt_pk_bf16(float lo, float hi) { unsigned r; asm volatile("v_cvt_pk_bf16_f32 %0, %1, %2" : "=v"(r) : "v"(lo), "v"(hi)); return r; }
; __device__ __forceinline__ float bf_lo(unsigned w) { return __uint_as_float(w << 16); }
; __device__ __forceinline__ float bf_hi(unsigned w) { return __uint_as_float(w & 0xffff0000u); }
; __device__ __forceinline__ float fast_sigmoid(float g) { return __builtin_amdgcn_rcpf(1.f + __builtin_amdgcn_exp2f(-g * LOG2E)); }
;     __device__ __forceinline__ void operator()(AccRef acc, const Unit& u, int wr, int wc, int fr, int fq, const LAS float* rsl) const {
;         const int row0 = u.pm * 256 + wr * 64 + fr, col0 = u.pn * 256 + wc * 32 + 8 * fq;
;         u32x4 xw[2], pw[2];
;         { const size_t off = (size_t)row0 * D + col0; xw[0] = *(const GAS u32x4*)(XI + off); pw[0] = *(const GAS u32x4*)(PP + off); }
;         float sq = 0.f;
; #pragma unroll
;         for (int t = 0; t < 16; ++t) {
;             const int ai = t >> 3, m = (t >> 1) & 3, bj = t & 1;
;             const int row = row0 + ai * 128 + m * 16;
;             const size_t off = (size_t)row * D + col0 + bj * 128;
;             if (t < 15) { const int t1 = t + 1, ai1 = t1 >> 3, m1 = (t1 >> 1) & 3, bj1 = t1 & 1;
;                 const size_t off1 = (size_t)(row0 + ai1 * 128 + m1 * 16) * D + col0 + bj1 * 128;
;                 xw[t1 & 1] = *(const GAS u32x4*)(XI + off1); pw[t1 & 1] = *(const GAS u32x4*)(PP + off1); }
;             const float rs = rsl[ai * 128 + wr * 64 + m * 16 + fr];
;             const u32x4 xv = xw[t & 1], pv = pw[t & 1];
;             const f32x4 g0 = acc[ai][bj][m][0] * rs, g1 = acc[ai][bj][m][1] * rs;
;             u32x4 w;
;             w.x = cvt_pk_bf16(bf_lo(xv.x) + fast_sigmoid(g0[0]) * bf_lo(pv.x), bf_hi(xv.x) + fast_sigmoid(g0[1]) * bf_hi(pv.x));
;             w.y = cvt_pk_bf16(bf_lo(xv.y) + fast_sigmoid(g0[2]) * bf_lo(pv.y), bf_hi(xv.y) + fast_sigmoid(g0[3]) * bf_hi(pv.y));
;             w.z = cvt_pk_bf16(bf_lo(xv.z) + fast_sigmoid(g1[0]) * bf_lo(pv.z), bf_hi(xv.z) + fast_sigmoid(g1[1]) * bf_hi(pv.z));
;             w.w = cvt_pk_bf16(bf_lo(xv.w) + fast_sigmoid(g1[2]) * bf_lo(pv.w), bf_hi(xv.w) + fast_sigmoid(g1[3]) * bf_hi(pv.w));
;             *(GAS u32x4*)(XO + off) = w;
.LBB0_249:
	v_lshl_add_u32 v160, s10, 8, v1
	v_lshl_or_b32 v158, s12, 8, v173
	v_ashrrev_i32_e32 v161, 31, v160
	v_ashrrev_i32_e32 v159, 31, v158
	v_lshlrev_b64 v[130:131], 10, v[160:161]
	v_lshl_add_u64 v[130:131], v[130:131], 0, v[158:159]
	v_readlane_b32 s58, v254, 55
	v_lshlrev_b64 v[130:131], 1, v[130:131]
	v_readlane_b32 s59, v254, 56
	v_lshl_add_u64 v[140:141], s[18:19], 0, v[130:131]
	s_lshl_b32 s25, s49, 10
	v_lshl_add_u64 v[138:139], s[58:59], 0, v[130:131]
	global_load_dwordx4 v[130:133], v[138:139], off
	global_load_dwordx4 v[134:137], v[140:141], off
	s_and_b32 s25, s25, 0x1c00
	v_lshlrev_b64 v[142:143], 11, v[160:161]
	v_add_u32_e32 v176, s25, v174
	v_lshl_add_u64 v[142:143], s[8:9], 0, v[142:143]
	ds_read_b32 v162, v176
	v_lshl_add_u64 v[170:171], v[158:159], 1, v[142:143]
	global_load_dwordx4 v[142:145], v[138:139], off offset:256
	global_load_dwordx4 v[166:169], v[140:141], off offset:256
	v_add_co_u32_e32 v184, vcc, 0x8000, v138
	v_addc_co_u32_e32 v185, vcc, 0, v139, vcc
	global_load_dword v177, v[184:185], off
	global_load_dword v177, v[184:185], off offset:256
	v_add_co_u32_e32 v186, vcc, 0x8000, v140
	v_addc_co_u32_e32 v187, vcc, 0, v141, vcc
	global_load_dword v177, v[186:187], off
	global_load_dword v177, v[186:187], off offset:256
	v_add_co_u32_e32 v184, vcc, 0x10000, v138
	v_addc_co_u32_e32 v185, vcc, 0, v139, vcc
	global_load_dword v177, v[184:185], off
	global_load_dword v177, v[184:185], off offset:256
	v_add_co_u32_e32 v186, vcc, 0x10000, v140
	v_addc_co_u32_e32 v187, vcc, 0, v141, vcc
	global_load_dword v177, v[186:187], off
	global_load_dword v177, v[186:187], off offset:256
	v_add_co_u32_e32 v184, vcc, 0x18000, v138
	v_addc_co_u32_e32 v185, vcc, 0, v139, vcc
	global_load_dword v177, v[184:185], off
	global_load_dword v177, v[184:185], off offset:256
	v_add_co_u32_e32 v186, vcc, 0x18000, v140
	v_addc_co_u32_e32 v187, vcc, 0, v141, vcc
	global_load_dword v177, v[186:187], off
	global_load_dword v177, v[186:187], off offset:256
	v_add_co_u32_e32 v184, vcc, 0x40000, v138
	v_addc_co_u32_e32 v185, vcc, 0, v139, vcc
	global_load_dword v177, v[184:185], off
	global_load_dword v177, v[184:185], off offset:256
	v_add_co_u32_e32 v186, vcc, 0x40000, v140
	v_addc_co_u32_e32 v187, vcc, 0, v141, vcc
	global_load_dword v177, v[186:187], off
	global_load_dword v177, v[186:187], off offset:256
	v_add_co_u32_e32 v184, vcc, 0x48000, v138
	v_addc_co_u32_e32 v185, vcc, 0, v139, vcc
	global_load_dword v177, v[184:185], off
	global_load_dword v177, v[184:185], off offset:256
	v_add_co_u32_e32 v186, vcc, 0x48000, v140
	v_addc_co_u32_e32 v187, vcc, 0, v141, vcc
	global_load_dword v177, v[186:187], off
	global_load_dword v177, v[186:187], off offset:256
	v_add_co_u32_e32 v184, vcc, 0x50000, v138
	v_addc_co_u32_e32 v185, vcc, 0, v139, vcc
	global_load_dword v177, v[184:185], off
	global_load_dword v177, v[184:185], off offset:256
	v_add_co_u32_e32 v186, vcc, 0x50000, v140
	v_addc_co_u32_e32 v187, vcc, 0, v141, vcc
	global_load_dword v177, v[186:187], off
	global_load_dword v177, v[186:187], off offset:256
	v_add_co_u32_e32 v184, vcc, 0x58000, v138
	v_addc_co_u32_e32 v185, vcc, 0, v139, vcc
	global_load_dword v177, v[184:185], off
	global_load_dword v177, v[184:185], off offset:256
	v_add_co_u32_e32 v186, vcc, 0x58000, v140
	v_addc_co_u32_e32 v187, vcc, 0, v141, vcc
	global_load_dword v177, v[186:187], off
	global_load_dword v177, v[186:187], off offset:256
	v_cmp_lt_i32_e32 vcc, v251, v253
	s_lshl_b32 s34, s12, 2
	s_waitcnt lgkmcnt(0)
	v_pk_mul_f32 v[138:139], v[128:129], v[162:163] op_sel_hi:[1,0]
	v_pk_mul_f32 v[140:141], v[126:127], v[162:163] op_sel_hi:[1,0]
	v_pk_mul_f32 v[164:165], v[124:125], v[162:163] op_sel_hi:[1,0]
	v_pk_mul_f32 v[162:163], v[122:123], v[162:163] op_sel_hi:[1,0]
	v_mul_f32_e32 v141, 0xbfb8aa3b, v141
	v_mul_f32_e32 v139, 0xbfb8aa3b, v139
	v_mul_f32_e32 v140, 0xbfb8aa3b, v140
	v_mul_f32_e32 v138, 0xbfb8aa3b, v138
	v_mul_f32_e32 v163, 0xbfb8aa3b, v163
	v_mul_f32_e32 v165, 0xbfb8aa3b, v165
	v_exp_f32_e32 v141, v141
	v_exp_f32_e32 v139, v139
	v_mul_f32_e32 v162, 0xbfb8aa3b, v162
	v_mul_f32_e32 v164, 0xbfb8aa3b, v164
	v_exp_f32_e32 v140, v140
	v_exp_f32_e32 v138, v138
	v_exp_f32_e32 v163, v163
	v_exp_f32_e32 v165, v165
	v_exp_f32_e32 v162, v162
	v_exp_f32_e32 v164, v164
	v_add_f32_e32 v141, 1.0, v141
	v_add_f32_e32 v139, 1.0, v139
	v_add_f32_e32 v140, 1.0, v140
	v_add_f32_e32 v138, 1.0, v138
	v_add_f32_e32 v163, 1.0, v163
	v_add_f32_e32 v165, 1.0, v165
	v_rcp_f32_e32 v141, v141
	v_rcp_f32_e32 v139, v139
	v_add_f32_e32 v162, 1.0, v162
	v_add_f32_e32 v164, 1.0, v164
	v_rcp_f32_e32 v140, v140
	v_rcp_f32_e32 v138, v138
	v_rcp_f32_e32 v163, v163
	v_rcp_f32_e32 v165, v165
	v_rcp_f32_e32 v162, v162
	v_rcp_f32_e32 v164, v164
	s_ashr_i32 s35, s34, 31
	s_waitcnt vmcnt(0)
; #define GAS __attribute__((address_space(1)))
; __device__ __forceinline__ unsigned cvt_pk_bf16(float lo, float hi) { unsigned r; asm volatile("v_cvt_pk_bf16_f32 %0, %1, %2" : "=v"(r) : "v"(lo), "v"(hi)); return r; }
; __device__ __forceinline__ float bf_lo(unsigned w) { return __uint_as_float(w << 16); }
; __device__ __forceinline__ float bf_hi(unsigned w) { return __uint_as_float(w & 0xffff0000u); }
; __device__ __forceinline__ float fast_sigmoid(float g) { return __builtin_amdgcn_rcpf(1.f + __builtin_amdgcn_exp2f(-g * LOG2E)); }
;     __device__ __forceinline__ void operator()(AccRef acc, const Unit& u, int wr, int wc, int fr, int fq, const LAS float* rsl) const {
;     ...
;         for (int t = 0; t < 16; ++t) {
;             const int ai = t >> 3, m = (t >> 1) & 3, bj = t & 1;
;             const int row = row0 + ai * 128 + m * 16;
;             const size_t off = (size_t)row * D + col0 + bj * 128;
;             if (t < 15) { const int t1 = t + 1, ai1 = t1 >> 3, m1 = (t1 >> 1) & 3, bj1 = t1 & 1;
;                 const size_t off1 = (size_t)(row0 + ai1 * 128 + m1 * 16) * D + col0 + bj1 * 128;
;                 xw[t1 & 1] = *(const GAS u32x4*)(XI + off1); pw[t1 & 1] = *(const GAS u32x4*)(PP + off1); }
;             const float rs = rsl[ai * 128 + wr * 64 + m * 16 + fr];
;             const u32x4 xv = xw[t & 1], pv = pw[t & 1];
;             const f32x4 g0 = acc[ai][bj][m][0] * rs, g1 = acc[ai][bj][m][1] * rs;
;             u32x4 w;
;             w.x = cvt_pk_bf16(bf_lo(xv.x) + fast_sigmoid(g0[0]) * bf_lo(pv.x), bf_hi(xv.x) + fast_sigmoid(g0[1]) * bf_hi(pv.x));
;             w.y = cvt_pk_bf16(bf_lo(xv.y) + fast_sigmoid(g0[2]) * bf_lo(pv.y), bf_hi(xv.y) + fast_sigmoid(g0[3]) * bf_hi(pv.y));
;             w.z = cvt_pk_bf16(bf_lo(xv.z) + fast_sigmoid(g1[0]) * bf_lo(pv.z), bf_hi(xv.z) + fast_sigmoid(g1[1]) * bf_hi(pv.z));
;             w.w = cvt_pk_bf16(bf_lo(xv.w) + fast_sigmoid(g1[2]) * bf_lo(pv.w), bf_hi(xv.w) + fast_sigmoid(g1[3]) * bf_hi(pv.w));
;             *(GAS u32x4*)(XO + off) = w;
;             sq += sq8(w);
;             if (bj == 1) {
;                 sq += __shfl_xor(sq, 16); sq += __shfl_xor(sq, 32);
;                 if (fq == 0) sso[(size_t)row * 16 + u.pn * 4 + wc] = sq;
;                 sq = 0.f;
;             }
;         }
	v_lshlrev_b32_e32 v177, 16, v130
	v_lshlrev_b32_e32 v180, 16, v134
	v_and_b32_e32 v130, 0xffff0000, v130
	v_and_b32_e32 v134, 0xffff0000, v134
	v_lshlrev_b32_e32 v181, 16, v131
	v_lshlrev_b32_e32 v183, 16, v135
	v_and_b32_e32 v131, 0xffff0000, v131
	v_and_b32_e32 v135, 0xffff0000, v135
	v_lshlrev_b32_e32 v184, 16, v132
	v_lshlrev_b32_e32 v185, 16, v136
	v_and_b32_e32 v132, 0xffff0000, v132
	v_and_b32_e32 v136, 0xffff0000, v136
	v_lshlrev_b32_e32 v186, 16, v133
	v_lshlrev_b32_e32 v187, 16, v137
	v_and_b32_e32 v133, 0xffff0000, v133
	v_and_b32_e32 v137, 0xffff0000, v137
	v_fmac_f32_e32 v130, v141, v134
	v_fmac_f32_e32 v131, v139, v135
	v_fmac_f32_e32 v177, v140, v180
	v_fmac_f32_e32 v181, v138, v183
	v_fmac_f32_e32 v132, v163, v136
	v_fmac_f32_e32 v133, v165, v137
	v_cvt_pk_bf16_f32 v130, v177, v130
	v_cvt_pk_bf16_f32 v131, v181, v131
	v_fmac_f32_e32 v184, v162, v185
	v_fmac_f32_e32 v186, v164, v187
	v_cvt_pk_bf16_f32 v132, v184, v132
	v_cvt_pk_bf16_f32 v133, v186, v133
	global_store_dwordx4 v[170:171], v[130:133], off
	v_lshlrev_b32_e32 v134, 16, v130
	v_lshlrev_b32_e32 v135, 16, v131
	v_and_b32_e32 v130, 0xffff0000, v130
	v_and_b32_e32 v131, 0xffff0000, v131
	v_mul_f32_e32 v130, v130, v130
	v_mul_f32_e32 v131, v131, v131
	v_lshlrev_b32_e32 v136, 16, v132
	v_and_b32_e32 v132, 0xffff0000, v132
	v_lshlrev_b32_e32 v137, 16, v133
	v_and_b32_e32 v133, 0xffff0000, v133
	v_fmac_f32_e32 v130, v134, v134
	v_fmac_f32_e32 v131, v135, v135
	v_add_f32_e32 v130, v130, v131
	v_mul_f32_e32 v131, v132, v132
	v_mul_f32_e32 v132, v133, v133
	v_fmac_f32_e32 v131, v136, v136
	v_fmac_f32_e32 v132, v137, v137
	v_or_b32_e32 v164, 16, v160
	v_add_f32_e32 v131, v131, v132
	v_ashrrev_i32_e32 v165, 31, v164
	v_add_f32_e32 v177, v130, v131
	v_lshlrev_b64 v[130:131], 10, v[164:165]
	v_lshl_add_u64 v[130:131], v[130:131], 0, v[158:159]
	v_lshlrev_b64 v[130:131], 1, v[130:131]
	v_lshl_add_u64 v[134:135], s[58:59], 0, v[130:131]
	v_lshl_add_u64 v[136:137], s[18:19], 0, v[130:131]
	global_load_dwordx4 v[138:141], v[134:135], off
	global_load_dwordx4 v[130:133], v[136:137], off
	ds_read_b32 v162, v176
	v_lshlrev_b32_e32 v188, 16, v166
	v_and_b32_e32 v166, 0xffff0000, v166
	s_waitcnt lgkmcnt(0)
	v_pk_mul_f32 v[184:185], v[94:95], v[162:163] op_sel_hi:[1,0]
	s_nop 0
	v_mul_f32_e32 v185, 0xbfb8aa3b, v185
	v_mul_f32_e32 v183, 0xbfb8aa3b, v184
	v_exp_f32_e32 v185, v185
	v_exp_f32_e32 v183, v183
	v_lshlrev_b32_e32 v184, 16, v142
	v_and_b32_e32 v142, 0xffff0000, v142
	v_add_f32_e32 v185, 1.0, v185
	v_add_f32_e32 v183, 1.0, v183
	v_rcp_f32_e32 v185, v185
	v_rcp_f32_e32 v183, v183
	v_pk_mul_f32 v[180:181], v[96:97], v[162:163] op_sel_hi:[1,0]
	v_pk_mul_f32 v[186:187], v[92:93], v[162:163] op_sel_hi:[1,0]
	v_fmac_f32_e32 v142, v185, v166
	v_fmac_f32_e32 v184, v183, v188
	v_cvt_pk_bf16_f32 v166, v184, v142
	v_mul_f32_e32 v142, 0xbfb8aa3b, v180
	v_exp_f32_e32 v142, v142
	v_mul_f32_e32 v181, 0xbfb8aa3b, v181
	v_exp_f32_e32 v181, v181
	v_lshlrev_b32_e32 v180, 16, v143
	v_add_f32_e32 v142, 1.0, v142
	v_rcp_f32_e32 v142, v142
	v_add_f32_e32 v181, 1.0, v181
	v_rcp_f32_e32 v181, v181
	v_lshlrev_b32_e32 v183, 16, v167
	v_fmac_f32_e32 v180, v142, v183
	v_and_b32_e32 v142, 0xffff0000, v143
	v_and_b32_e32 v143, 0xffff0000, v167
	v_pk_mul_f32 v[162:163], v[90:91], v[162:163] op_sel_hi:[1,0]
	v_fmac_f32_e32 v142, v181, v143
	v_cvt_pk_bf16_f32 v167, v180, v142
	v_mul_f32_e32 v142, 0xbfb8aa3b, v162
	v_exp_f32_e32 v142, v142
	v_mul_f32_e32 v162, 0xbfb8aa3b, v163
	v_exp_f32_e32 v162, v162
	v_lshlrev_b32_e32 v143, 16, v144
	v_add_f32_e32 v142, 1.0, v142
	v_rcp_f32_e32 v142, v142
	v_add_f32_e32 v162, 1.0, v162
	v_rcp_f32_e32 v162, v162
	v_lshlrev_b32_e32 v163, 16, v168
	v_fmac_f32_e32 v143, v142, v163
	v_and_b32_e32 v142, 0xffff0000, v144
	v_and_b32_e32 v144, 0xffff0000, v168
	v_fmac_f32_e32 v142, v162, v144
	v_cvt_pk_bf16_f32 v168, v143, v142
	v_mul_f32_e32 v142, 0xbfb8aa3b, v186
	v_exp_f32_e32 v142, v142
	v_mul_f32_e32 v144, 0xbfb8aa3b, v187
	v_exp_f32_e32 v144, v144
	v_lshlrev_b32_e32 v143, 16, v145
	v_add_f32_e32 v142, 1.0, v142
	v_rcp_f32_e32 v142, v142
	v_add_f32_e32 v144, 1.0, v144
	v_rcp_f32_e32 v144, v144
	v_lshlrev_b32_e32 v162, 16, v169
	v_fmac_f32_e32 v143, v142, v162
	v_and_b32_e32 v142, 0xffff0000, v145
	v_and_b32_e32 v145, 0xffff0000, v169
	v_fmac_f32_e32 v142, v144, v145
	v_cvt_pk_bf16_f32 v169, v143, v142
	v_and_b32_e32 v143, 0xffff0000, v166
	v_lshlrev_b32_e32 v142, 16, v166
	v_mul_f32_e32 v143, v143, v143
	v_and_b32_e32 v144, 0xffff0000, v167
	v_fmac_f32_e32 v143, v142, v142
	v_lshlrev_b32_e32 v142, 16, v167
	v_mul_f32_e32 v144, v144, v144
	v_fmac_f32_e32 v144, v142, v142
	v_add_f32_e32 v142, v143, v144
	v_and_b32_e32 v144, 0xffff0000, v168
	v_lshlrev_b32_e32 v143, 16, v168
	v_mul_f32_e32 v144, v144, v144
	v_and_b32_e32 v145, 0xffff0000, v169
	v_fmac_f32_e32 v144, v143, v143
	v_lshlrev_b32_e32 v143, 16, v169
	v_mul_f32_e32 v145, v145, v145
	v_fmac_f32_e32 v145, v143, v143
	v_add_f32_e32 v143, v144, v145
	v_add_f32_e32 v142, v142, v143
	v_cndmask_b32_e32 v143, v246, v251, vcc
	v_add_f32_e32 v142, v177, v142
	v_lshlrev_b32_e32 v177, 2, v143
	ds_bpermute_b32 v143, v177, v142
	v_cmp_lt_i32_e32 vcc, v252, v253
	global_store_dwordx4 v[170:171], v[166:169], off offset:256
	s_waitcnt lgkmcnt(0)
	v_add_f32_e32 v142, v142, v143
	v_cndmask_b32_e32 v143, v246, v252, vcc
	v_lshlrev_b32_e32 v190, 2, v143
	ds_bpermute_b32 v143, v190, v142
	s_and_saveexec_b64 s[36:37], s[2:3]
	s_cbranch_execz .LBB0_251
	v_lshlrev_b64 v[144:145], 6, v[160:161]
	v_lshl_add_u64 v[144:145], s[16:17], 0, v[144:145]
	v_lshl_add_u64 v[144:145], s[34:35], 2, v[144:145]
	s_lshl_b32 s90, s45, 2
	v_lshl_add_u64 v[144:145], v[144:145], 0, s[90:91]
	s_waitcnt lgkmcnt(0)
	v_add_f32_e32 v142, v142, v143
	global_store_dword v[144:145], v142, off
